# v42 + MLA loop bottom: fmamk straight to exp dst; 16 v_exp + 8 v_fma moved across back-edge to loop top (LDS latency window, first QK gaps); entry copy of half 1, exit fix-up
# baseline (speedup 1.0000x reference)
.LBB0_542:
	v_cndmask_b32_e64 v202, v50, v1, s[2:3]
	v_mul_f32_e32 v50, 0xbdd53b94, v202
	v_fmamk_f32 v35, v35, 0x3dd53b94, v50
	v_fmamk_f32 v34, v34, 0x3dd53b94, v50
	v_fmamk_f32 v36, v36, 0x3dd53b94, v50
	v_exp_f32_e32 v231, v35
	v_lshlrev_b32_e32 v35, 4, v161
	v_exp_f32_e32 v229, v34
	v_exp_f32_e32 v227, v36
	v_lshlrev_b32_e32 v34, 3, v161
	v_and_b32_e32 v35, 0xc0, v35
	v_lshlrev_b32_e32 v36, 1, v161
	v_and_or_b32 v35, v34, 24, v35
	v_and_b32_e32 v36, 32, v36
	v_and_b32_e32 v34, 0x100, v34
	s_cmp_lg_u32 0, -1
	v_fmamk_f32 v37, v37, 0x3dd53b94, v50
	v_fmamk_f32 v38, v38, 0x3dd53b94, v50
	v_fmamk_f32 v39, v39, 0x3dd53b94, v50
	v_fmamk_f32 v40, v40, 0x3dd53b94, v50
	v_fmamk_f32 v41, v41, 0x3dd53b94, v50
	v_fmamk_f32 v42, v42, 0x3dd53b94, v50
	v_fmamk_f32 v43, v43, 0x3dd53b94, v50
	v_fmamk_f32 v44, v44, 0x3dd53b94, v50
	v_fmamk_f32 v45, v45, 0x3dd53b94, v50
	v_fmamk_f32 v46, v46, 0x3dd53b94, v50
	v_fmamk_f32 v47, v47, 0x3dd53b94, v50
	v_fmamk_f32 v48, v48, 0x3dd53b94, v50
	v_fmamk_f32 v49, v49, 0x3dd53b94, v50
	v_or3_b32 v34, v35, v36, v34
	s_cselect_b32 s1, 0, 0
	v_exp_f32_e32 v230, v37
	v_exp_f32_e32 v226, v38
	v_exp_f32_e32 v228, v39
	v_exp_f32_e32 v224, v40
	v_exp_f32_e32 v225, v41
	v_exp_f32_e32 v221, v42
	v_exp_f32_e32 v223, v43
	v_exp_f32_e32 v220, v44
	v_exp_f32_e32 v222, v45
	v_exp_f32_e32 v217, v46
	v_exp_f32_e32 v219, v47
	v_exp_f32_e32 v216, v48
	v_exp_f32_e32 v218, v49
	v_add_u32_e32 v200, s1, v34
	s_and_b32 s1, s84, 7
	s_lshl_b32 s1, s1, 9
	s_waitcnt vmcnt(0)
	v_pk_fma_f32 v[146:147], v[32:33], s[34:35], v[50:51] op_sel_hi:[1,0,0]
	v_pk_fma_f32 v[148:149], v[30:31], s[34:35], v[50:51] op_sel_hi:[1,0,0]
	v_pk_fma_f32 v[150:151], v[28:29], s[34:35], v[50:51] op_sel_hi:[1,0,0]
	v_pk_fma_f32 v[152:153], v[26:27], s[34:35], v[50:51] op_sel_hi:[1,0,0]
	v_pk_fma_f32 v[154:155], v[24:25], s[34:35], v[50:51] op_sel_hi:[1,0,0]
	v_pk_fma_f32 v[156:157], v[22:23], s[34:35], v[50:51] op_sel_hi:[1,0,0]
	v_pk_fma_f32 v[162:163], v[20:21], s[34:35], v[50:51] op_sel_hi:[1,0,0]
	v_pk_fma_f32 v[164:165], v[18:19], s[34:35], v[50:51] op_sel_hi:[1,0,0]
	v_lshl_add_u32 v170, v168, 2, v51
	v_lshl_add_u32 v158, v52, 2, v51
	s_add_u32 s20, s4, s1
	v_mov_b64_e32 v[64:65], v[16:17]
	v_mov_b64_e32 v[48:49], v[16:17]
	v_mov_b64_e32 v[32:33], v[16:17]
	s_mov_b32 s17, 1
	s_mov_b32 s0, 0
	v_cmp_gt_u32_e64 s[2:3], 32, v161
	s_mov_b32 s19, 2
	s_addc_u32 s21, s5, 0
	v_mov_b32_e32 v171, 0
	v_mov_b64_e32 v[62:63], v[14:15]
	v_mov_b64_e32 v[60:61], v[12:13]
	v_mov_b64_e32 v[58:59], v[10:11]
	v_mov_b64_e32 v[56:57], v[8:9]
	v_mov_b64_e32 v[54:55], v[6:7]
	v_mov_b64_e32 v[52:53], v[4:5]
	v_mov_b64_e32 v[50:51], v[2:3]
	v_mov_b64_e32 v[46:47], v[14:15]
	v_mov_b64_e32 v[44:45], v[12:13]
	v_mov_b64_e32 v[42:43], v[10:11]
	v_mov_b64_e32 v[40:41], v[8:9]
	v_mov_b64_e32 v[38:39], v[6:7]
	v_mov_b64_e32 v[36:37], v[4:5]
	v_mov_b64_e32 v[34:35], v[2:3]
	v_mov_b64_e32 v[30:31], v[14:15]
	v_mov_b64_e32 v[28:29], v[12:13]
	v_mov_b64_e32 v[26:27], v[10:11]
	v_mov_b64_e32 v[24:25], v[8:9]
	v_mov_b64_e32 v[22:23], v[6:7]
	v_mov_b64_e32 v[20:21], v[4:5]
	v_mov_b64_e32 v[18:19], v[2:3]
	s_mov_b32 s22, 2
	s_waitcnt vmcnt(0)
	s_barrier
	v_mov_b32_e32 v245, v172
	v_ashrrev_i32_e32 v250, 4, v245
	v_xor_b32_e32 v246, v250, v245
	v_lshlrev_b32_e32 v246, 3, v246
	v_lshrrev_b32_e32 v247, 1, v245
	v_and_b32_e32 v246, 0x78, v246
	v_and_b32_e32 v255, 8, v247
	v_lshrrev_b32_e32 v247, 1, v250
	v_bfe_u32 v254, v245, 2, 2
	v_and_b32_e32 v248, 4, v247
	v_lshl_or_b32 v246, v250, 11, v246
	v_and_or_b32 v250, v250, s75, v255
	v_lshlrev_b32_e32 v247, 3, v245
	v_or3_b32 v250, v250, v248, v254
	v_and_b32_e32 v251, 0x60, v245
	v_and_b32_e32 v249, 24, v247
	v_lshlrev_b32_e32 v250, 11, v250
	v_or3_b32 v250, v250, v251, v249
	v_ashrrev_i32_e32 v247, 31, v246
	v_ashrrev_i32_e32 v251, 31, v250
	v_lshlrev_b64 v[246:247], 1, v[246:247]
	v_lshlrev_b64 v[248:249], 1, v[250:251]
	v_lshrrev_b32_e32 v255, 4, v245
	v_lshrrev_b32_e32 v254, 3, v245
	v_xor_b32_e32 v255, v255, v245
	v_mul_lo_u32 v254, v254, s76
	v_lshlrev_b32_e32 v255, 3, v255
	v_and_or_b32 v254, v255, 56, v254
	v_ashrrev_i32_e32 v255, 31, v254
	v_lshlrev_b64 v[250:251], 1, v[254:255]
	s_mov_b32 s23, s17
	s_mov_b32 s17, s0
	s_add_i32 s71, 0, 0x10000
	ds_read_b128 v[66:69], v174 offset:49152
	ds_read_b128 v[70:73], v174 offset:57344
	ds_read_b128 v[206:209], v176 offset:49152
	ds_read_b128 v[210:213], v176 offset:57344
	s_waitcnt lgkmcnt(0)
	v_mfma_f32_32x32x16_bf16 v[82:97], v[66:69], v[142:145], 0
	s_add_i32 s0, 0, 0x16000
	v_exp_f32_e32 v240, v146
	v_add_f32_e32 v146, 0, v229
	v_add_f32_e32 v146, v231, v146
	v_add_f32_e32 v146, v227, v146
	v_add_f32_e32 v146, v230, v146
	v_add_f32_e32 v146, v226, v146
	v_mfma_f32_32x32x16_bf16 v[66:81], v[70:73], v[142:145], 0
	v_add_f32_e32 v146, v228, v146
	v_add_f32_e32 v146, v224, v146
	v_add_f32_e32 v146, v225, v146
	v_add_f32_e32 v146, v221, v146
	v_add_f32_e32 v146, v223, v146
	v_add_f32_e32 v146, v220, v146
	v_add_f32_e32 v146, v222, v146
	v_mfma_f32_32x32x16_bf16 v[82:97], v[206:209], v[138:141], v[82:97]
	v_exp_f32_e32 v164, v164
	v_add_f32_e32 v146, v217, v146
	v_exp_f32_e32 v165, v165
	v_add_f32_e32 v146, v219, v146
	v_exp_f32_e32 v197, v162
	v_add_f32_e32 v146, v216, v146
	v_add_f32_e32 v146, v218, v146
	v_mfma_f32_32x32x16_bf16 v[66:81], v[210:213], v[138:141], v[66:81]
	ds_read_b128 v[206:209], v178 offset:49152
	ds_read_b128 v[210:213], v178 offset:57344
	s_add_u32 s4, s38, s20
	s_addc_u32 s5, s39, s21
	s_add_u32 s24, s4, 0x149ec400
	s_addc_u32 s25, s5, 0
	s_mov_b32 m0, s90
	v_lshl_add_u64 v[254:255], v[246:247], 0, s[24:25]
	s_lshl_b32 s18, s22, 14
	global_load_lds_dwordx4 v[254:255], off
	s_add_u32 s24, s4, 0x14a0c400
	s_addc_u32 s25, s5, 0
	s_mov_b32 m0, s91
	v_lshl_add_u64 v[254:255], v[246:247], 0, s[24:25]
	s_add_i32 s1, s89, s18
	global_load_lds_dwordx4 v[254:255], off
	s_add_u32 s24, s4, 0x149ec500
	s_addc_u32 s25, s5, 0
	s_mov_b32 m0, s1
	v_lshl_add_u64 v[254:255], v[248:249], 0, s[24:25]
	global_load_lds_dwordx4 v[254:255], off
	s_add_u32 s24, s4, 0x14a0c500
	s_addc_u32 s25, s5, 0
	s_add_i32 m0, s1, 0x2000
	v_lshl_add_u64 v[254:255], v[248:249], 0, s[24:25]
	global_load_lds_dwordx4 v[254:255], off
	s_add_u32 s4, s38, s88
	s_addc_u32 s5, s39, s87
	s_add_u32 s4, s4, s36
	s_addc_u32 s5, s5, s37
	s_mov_b32 m0, s92
	v_lshl_add_u64 v[254:255], v[250:251], 0, s[4:5]
	global_load_lds_dwordx4 v[254:255], off
	v_exp_f32_e32 v156, v156
	v_add_f32_e32 v146, v164, v146
	v_exp_f32_e32 v157, v157
	v_add_f32_e32 v146, v165, v146
	v_add_f32_e32 v146, v197, v146
	v_exp_f32_e32 v241, v147
	s_waitcnt lgkmcnt(0)
	v_mfma_f32_32x32x16_bf16 v[82:97], v[206:209], v[134:137], v[82:97]
	v_mfma_f32_32x32x16_bf16 v[66:81], v[210:213], v[134:137], v[66:81]
	ds_read_b128 v[208:211], v180 offset:49152
	ds_read_b128 v[212:215], v180 offset:57344
	s_waitcnt lgkmcnt(0)
	v_mfma_f32_32x32x16_bf16 v[82:97], v[208:211], v[130:133], v[82:97]
	v_mfma_f32_32x32x16_bf16 v[66:81], v[212:215], v[130:133], v[66:81]
	ds_read_b128 v[208:211], v182 offset:49152
	ds_read_b128 v[212:215], v182 offset:57344
	s_waitcnt lgkmcnt(0)
	v_mfma_f32_32x32x16_bf16 v[82:97], v[208:211], v[126:129], v[82:97]
	v_mfma_f32_32x32x16_bf16 v[66:81], v[212:215], v[126:129], v[66:81]
	ds_read_b128 v[210:213], v186 offset:49152
	ds_read_b128 v[232:235], v186 offset:57344
	s_waitcnt lgkmcnt(0)
	v_mfma_f32_32x32x16_bf16 v[82:97], v[210:213], v[122:125], v[82:97]
	v_mfma_f32_32x32x16_bf16 v[66:81], v[232:235], v[122:125], v[66:81]
	ds_read_b128 v[210:213], v188 offset:49152
	ds_read_b128 v[232:235], v188 offset:57344
	s_waitcnt lgkmcnt(0)
	v_mfma_f32_32x32x16_bf16 v[82:97], v[210:213], v[118:121], v[82:97]
	v_mfma_f32_32x32x16_bf16 v[66:81], v[232:235], v[118:121], v[66:81]
	ds_read_b128 v[212:215], v190 offset:49152
	ds_read_b128 v[232:235], v190 offset:57344
	s_waitcnt lgkmcnt(0)
	v_mfma_f32_32x32x16_bf16 v[82:97], v[212:215], v[114:117], v[82:97]
	v_mfma_f32_32x32x16_bf16 v[66:81], v[232:235], v[114:117], v[66:81]
	ds_read_b128 v[212:215], v192 offset:8192
	ds_read_b128 v[232:235], v192 offset:12288
	s_waitcnt lgkmcnt(0)
	v_mfma_f32_32x32x16_bf16 v[82:97], v[212:215], v[110:113], v[82:97]
	v_exp_f32_e32 v215, v163
	s_nop 0
	v_add_f32_e32 v146, v215, v146
	v_mfma_f32_32x32x16_bf16 v[66:81], v[232:235], v[110:113], v[66:81]
	ds_read_b128 v[232:235], v194 offset:8192
	ds_read_b128 v[236:239], v194 offset:12288
	v_add_f32_e32 v146, v156, v146
	v_add_f32_e32 v146, v157, v146
	s_waitcnt lgkmcnt(0)
	v_mfma_f32_32x32x16_bf16 v[82:97], v[232:235], v[106:109], v[82:97]
	v_mfma_f32_32x32x16_bf16 v[66:81], v[236:239], v[106:109], v[66:81]
	ds_read_b128 v[232:235], v196 offset:8192
	ds_read_b128 v[236:239], v196 offset:12288
	s_waitcnt lgkmcnt(0)
	v_mfma_f32_32x32x16_bf16 v[82:97], v[232:235], v[102:105], v[82:97]
	v_mfma_f32_32x32x16_bf16 v[66:81], v[236:239], v[102:105], v[66:81]
	ds_read_b128 v[232:235], v199 offset:8192
	ds_read_b128 v[236:239], v199 offset:12288
	s_waitcnt lgkmcnt(0)
	v_mfma_f32_32x32x16_bf16 v[82:97], v[232:235], v[98:101], v[82:97]
	v_exp_f32_e32 v232, v154
	v_exp_f32_e32 v233, v155
	v_exp_f32_e32 v234, v152
	v_exp_f32_e32 v235, v153
	v_add_f32_e32 v146, v232, v146
	v_add_f32_e32 v146, v233, v146
	v_add_f32_e32 v146, v234, v146
	v_mfma_f32_32x32x16_bf16 v[66:81], v[236:239], v[98:101], v[66:81]
	v_exp_f32_e32 v236, v150
	v_exp_f32_e32 v237, v151
	v_exp_f32_e32 v238, v148
	v_exp_f32_e32 v239, v149
	v_add_f32_e32 v146, v235, v146
	v_add_f32_e32 v146, v236, v146
	v_add_f32_e32 v146, v237, v146
	v_add_f32_e32 v146, v238, v146
	v_add_f32_e32 v146, v239, v146
	v_add_f32_e32 v146, v240, v146
	v_add_f32_e32 v162, v241, v146
	v_mov_b32_e32 v163, v162
	s_nop 1
	v_permlane32_swap_b32_e32 v162, v163
	v_cvt_pk_bf16_f32 v146, v229, v231
	v_cvt_pk_bf16_f32 v147, v227, v230
	v_cvt_pk_bf16_f32 v148, v226, v228
	v_cvt_pk_bf16_f32 v149, v224, v225
	v_cvt_pk_bf16_f32 v150, v221, v223
	v_cvt_pk_bf16_f32 v151, v220, v222
	v_cvt_pk_bf16_f32 v152, v217, v219
	v_cvt_pk_bf16_f32 v153, v216, v218
	v_cvt_pk_bf16_f32 v154, v164, v165
	v_cvt_pk_bf16_f32 v155, v197, v215
	v_cvt_pk_bf16_f32 v156, v156, v157
	v_cvt_pk_bf16_f32 v157, v232, v233
	v_cvt_pk_bf16_f32 v216, v234, v235
	v_cvt_pk_bf16_f32 v217, v236, v237
	v_cvt_pk_bf16_f32 v218, v238, v239
	v_cvt_pk_bf16_f32 v219, v240, v241
	s_nop 0
	v_permlane32_swap_b32_e32 v146, v148
	v_permlane32_swap_b32_e32 v147, v149
	v_permlane32_swap_b32_e32 v150, v152
	v_permlane32_swap_b32_e32 v151, v153
	v_permlane32_swap_b32_e32 v154, v156
	v_permlane32_swap_b32_e32 v155, v157
	v_permlane32_swap_b32_e32 v216, v218
	v_permlane32_swap_b32_e32 v217, v219
	s_lshl_b32 s24, s17, 14
	v_add_u32_e32 v197, s24, v200
	ds_read_b64_tr_b16 v[220:221], v197 offset:0
	ds_read_b64_tr_b16 v[222:223], v197 offset:0x800
	ds_read_b64_tr_b16 v[224:225], v197 offset:0x1000
	ds_read_b64_tr_b16 v[226:227], v197 offset:0x1800
	ds_read_b64_tr_b16 v[228:229], v197 offset:0x2000
	ds_read_b64_tr_b16 v[230:231], v197 offset:0x2800
	ds_read_b64_tr_b16 v[232:233], v197 offset:0x3000
	ds_read_b64_tr_b16 v[234:235], v197 offset:0x3800
	s_waitcnt lgkmcnt(0)
	s_nop 0
	v_mfma_f32_32x32x16_bf16 v[2:17], v[146:149], v[220:223], v[2:17]
	ds_read_b64_tr_b16 v[220:221], v197 offset:0x200
	ds_read_b64_tr_b16 v[222:223], v197 offset:0xa00
	v_max_f32_e32 v164, v83, v83
	v_max_f32_e32 v165, v82, v82
	v_max_f32_e32 v164, v165, v164
	v_max3_f32 v164, v164, v84, v85
	v_max3_f32 v164, v164, v86, v87
	v_mfma_f32_32x32x16_bf16 v[2:17], v[150:153], v[224:227], v[2:17]
	ds_read_b64_tr_b16 v[224:225], v197 offset:0x1200
	ds_read_b64_tr_b16 v[226:227], v197 offset:0x1a00
	v_max3_f32 v164, v164, v88, v89
	v_max3_f32 v164, v164, v90, v91
	v_max3_f32 v164, v164, v92, v93
	v_max3_f32 v164, v164, v94, v95
	v_max3_f32 v164, v164, v96, v97
	v_mfma_f32_32x32x16_bf16 v[2:17], v[154:157], v[228:231], v[2:17]
	ds_read_b64_tr_b16 v[228:229], v197 offset:0x2200
	ds_read_b64_tr_b16 v[230:231], v197 offset:0x2a00
	ds_read_b64_tr_b16 v[236:237], v197 offset:0x3200
	ds_read_b64_tr_b16 v[238:239], v197 offset:0x3a00
	s_waitcnt lgkmcnt(0)
	v_mfma_f32_32x32x16_bf16 v[2:17], v[216:219], v[232:235], v[2:17]
	v_mfma_f32_32x32x16_bf16 v[50:65], v[146:149], v[220:223], v[50:65]
	v_max3_f32 v164, v164, v66, v67
	v_max3_f32 v164, v164, v68, v69
	v_max3_f32 v164, v164, v70, v71
	v_max3_f32 v164, v164, v72, v73
	v_max3_f32 v164, v164, v74, v75
	v_max3_f32 v164, v164, v76, v77
	v_max3_f32 v164, v164, v78, v79
	v_mfma_f32_32x32x16_bf16 v[50:65], v[150:153], v[224:227], v[50:65]
	v_max3_f32 v164, v164, v80, v81
	v_mov_b32_e32 v165, v164
	s_nop 1
	v_permlane32_swap_b32_e32 v164, v165
	ds_read_b64_tr_b16 v[220:221], v197 offset:0x400
	v_max_f32_e32 v165, v165, v165
	v_max_f32_e32 v164, v164, v164
	v_mfma_f32_32x32x16_bf16 v[50:65], v[154:157], v[228:231], v[50:65]
	ds_read_b64_tr_b16 v[222:223], v197 offset:0xc00
	v_max_f32_e32 v164, v164, v165
	v_max_f32_e32 v165, v202, v202
	ds_read_b64_tr_b16 v[224:225], v197 offset:0x1400
	v_max_f32_e32 v165, v165, v164
	ds_read_b64_tr_b16 v[226:227], v197 offset:0x1c00
	v_sub_f32_e32 v215, v164, v202
	v_mfma_f32_32x32x16_bf16 v[50:65], v[216:219], v[236:239], v[50:65]
	v_sub_f32_e32 v164, v202, v165
	ds_read_b64_tr_b16 v[228:229], v197 offset:0x2400
	v_mul_f32_e32 v164, 0x3dd53b94, v164
	ds_read_b64_tr_b16 v[230:231], v197 offset:0x2c00
	v_exp_f32_e32 v164, v164
	ds_read_b64_tr_b16 v[232:233], v197 offset:0x3400
	v_cmp_ge_f32_e32 vcc, s77, v215
	ds_read_b64_tr_b16 v[234:235], v197 offset:0x3c00
	s_cmp_eq_u64 vcc, exec
	s_waitcnt lgkmcnt(0)
	s_cselect_b64 s[4:5], -1, 0
	v_cndmask_b32_e64 v164, v164, 1.0, s[4:5]
	v_mfma_f32_32x32x16_bf16 v[34:49], v[146:149], v[220:223], v[34:49]
	ds_read_b64_tr_b16 v[220:221], v197 offset:0x600
	ds_read_b64_tr_b16 v[222:223], v197 offset:0xe00
	v_mfma_f32_32x32x16_bf16 v[34:49], v[150:153], v[224:227], v[34:49]
	ds_read_b64_tr_b16 v[224:225], v197 offset:0x1600
	ds_read_b64_tr_b16 v[226:227], v197 offset:0x1e00
	v_mfma_f32_32x32x16_bf16 v[34:49], v[154:157], v[228:231], v[34:49]
	ds_read_b64_tr_b16 v[228:229], v197 offset:0x2600
	ds_read_b64_tr_b16 v[230:231], v197 offset:0x2e00
	ds_read_b64_tr_b16 v[236:237], v197 offset:0x3600
	ds_read_b64_tr_b16 v[238:239], v197 offset:0x3e00
	s_waitcnt lgkmcnt(0)
	v_mfma_f32_32x32x16_bf16 v[34:49], v[216:219], v[232:235], v[34:49]
	v_mfma_f32_32x32x16_bf16 v[18:33], v[146:149], v[220:223], v[18:33]
	v_cmp_gt_f32_e32 vcc, 1.0, v164
	v_mfma_f32_32x32x16_bf16 v[18:33], v[150:153], v[224:227], v[18:33]
	v_mfma_f32_32x32x16_bf16 v[18:33], v[154:157], v[228:231], v[18:33]
	v_mfma_f32_32x32x16_bf16 v[18:33], v[216:219], v[236:239], v[18:33]
	s_cbranch_vccz .Lmla_e_547
	s_and_saveexec_b64 s[0:1], s[2:3]
	ds_write_b32 v170, v164 offset:128
	s_or_b64 exec, exec, s[0:1]
	s_waitcnt lgkmcnt(0)
	ds_read_b128 v[146:149], v158 offset:224
	ds_read_b128 v[150:153], v158 offset:192
	ds_read_b128 v[154:157], v158 offset:160
	ds_read_b128 v[216:219], v158 offset:128
	s_waitcnt lgkmcnt(0)
	v_pk_mul_f32 v[16:17], v[16:17], v[148:149]
	v_pk_mul_f32 v[12:13], v[12:13], v[152:153]
	v_pk_mul_f32 v[8:9], v[8:9], v[156:157]
	v_pk_mul_f32 v[4:5], v[4:5], v[218:219]
	v_pk_mul_f32 v[14:15], v[14:15], v[146:147]
	v_pk_mul_f32 v[10:11], v[10:11], v[150:151]
	v_pk_mul_f32 v[6:7], v[6:7], v[154:155]
	v_pk_mul_f32 v[2:3], v[2:3], v[216:217]
	v_pk_mul_f32 v[64:65], v[64:65], v[148:149]
	v_pk_mul_f32 v[60:61], v[60:61], v[152:153]
	v_pk_mul_f32 v[56:57], v[56:57], v[156:157]
	v_pk_mul_f32 v[52:53], v[52:53], v[218:219]
	v_pk_mul_f32 v[62:63], v[62:63], v[146:147]
	v_pk_mul_f32 v[58:59], v[58:59], v[150:151]
	v_pk_mul_f32 v[54:55], v[54:55], v[154:155]
	v_pk_mul_f32 v[50:51], v[50:51], v[216:217]
	v_pk_mul_f32 v[48:49], v[48:49], v[148:149]
	v_pk_mul_f32 v[44:45], v[44:45], v[152:153]
	v_pk_mul_f32 v[40:41], v[40:41], v[156:157]
	v_pk_mul_f32 v[36:37], v[36:37], v[218:219]
	v_pk_mul_f32 v[46:47], v[46:47], v[146:147]
	v_pk_mul_f32 v[42:43], v[42:43], v[150:151]
	v_pk_mul_f32 v[38:39], v[38:39], v[154:155]
	v_pk_mul_f32 v[34:35], v[34:35], v[216:217]
	v_pk_mul_f32 v[32:33], v[32:33], v[148:149]
	v_pk_mul_f32 v[28:29], v[28:29], v[152:153]
	v_pk_mul_f32 v[24:25], v[24:25], v[156:157]
	v_pk_mul_f32 v[20:21], v[20:21], v[218:219]
	v_pk_mul_f32 v[30:31], v[30:31], v[146:147]
	v_pk_mul_f32 v[26:27], v[26:27], v[150:151]
	v_pk_mul_f32 v[22:23], v[22:23], v[154:155]
	v_pk_mul_f32 v[18:19], v[18:19], v[216:217]
.Lmla_e_547:
	s_waitcnt vmcnt(0)
	s_add_i32 s0, s19, 1
	s_cmp_ge_u32 s0, s86
	s_cselect_b32 s98, 1, 0
	s_waitcnt vmcnt(0)
	s_barrier
	s_branch .LBB0_549
.LBB0_543:
	s_mov_b32 s23, s17
	s_mov_b32 s17, s0
	s_add_i32 s71, 0, 0x10000
	ds_read_b128 v[66:69], v174 offset:49152
	ds_read_b128 v[70:73], v174 offset:57344
	ds_read_b128 v[206:209], v176 offset:49152
	ds_read_b128 v[210:213], v176 offset:57344
	v_fma_f32 v152, v74, s34, v146
	v_fma_f32 v153, v75, s34, v146
	v_fma_f32 v150, v76, s34, v146
	v_fma_f32 v151, v77, s34, v146
	v_fma_f32 v148, v78, s34, v146
	v_fma_f32 v149, v79, s34, v146
	v_fma_f32 v147, v81, s34, v146
	v_fma_f32 v146, v80, s34, v146
	v_exp_f32_e32 v229, v229
	v_exp_f32_e32 v231, v231
	v_exp_f32_e32 v227, v227
	v_exp_f32_e32 v230, v230
	v_exp_f32_e32 v226, v226
	v_exp_f32_e32 v228, v228
	s_waitcnt lgkmcnt(0)
	v_mfma_f32_32x32x16_bf16 v[82:97], v[66:69], v[142:145], 0
	s_add_i32 s0, 0, 0x16000
	v_exp_f32_e32 v240, v146
	v_add_f32_e32 v146, 0, v229
	v_add_f32_e32 v146, v231, v146
	v_add_f32_e32 v146, v227, v146
	v_add_f32_e32 v146, v230, v146
	v_add_f32_e32 v146, v226, v146
	v_exp_f32_e32 v224, v224
	v_exp_f32_e32 v225, v225
	v_exp_f32_e32 v221, v221
	v_exp_f32_e32 v223, v223
	v_mfma_f32_32x32x16_bf16 v[66:81], v[70:73], v[142:145], 0
	v_exp_f32_e32 v220, v220
	v_exp_f32_e32 v222, v222
	v_add_f32_e32 v146, v228, v146
	v_add_f32_e32 v146, v224, v146
	v_add_f32_e32 v146, v225, v146
	v_add_f32_e32 v146, v221, v146
	v_add_f32_e32 v146, v223, v146
	v_add_f32_e32 v146, v220, v146
	v_add_f32_e32 v146, v222, v146
	v_exp_f32_e32 v217, v217
	v_exp_f32_e32 v219, v219
	v_exp_f32_e32 v216, v216
	v_exp_f32_e32 v218, v218
	v_mfma_f32_32x32x16_bf16 v[82:97], v[206:209], v[138:141], v[82:97]
	v_exp_f32_e32 v164, v164
	v_add_f32_e32 v146, v217, v146
	v_exp_f32_e32 v165, v165
	v_add_f32_e32 v146, v219, v146
	v_exp_f32_e32 v197, v162
	v_add_f32_e32 v146, v216, v146
	v_add_f32_e32 v146, v218, v146
	v_mfma_f32_32x32x16_bf16 v[66:81], v[210:213], v[138:141], v[66:81]
	ds_read_b128 v[206:209], v178 offset:49152
	ds_read_b128 v[210:213], v178 offset:57344
	s_add_u32 s4, s38, s20
	s_addc_u32 s5, s39, s21
	s_add_u32 s24, s4, 0x149ec400
	s_addc_u32 s25, s5, 0
	s_mov_b32 m0, s90
	v_lshl_add_u64 v[254:255], v[246:247], 0, s[24:25]
	s_lshl_b32 s18, s22, 14
	global_load_lds_dwordx4 v[254:255], off
	s_add_u32 s24, s4, 0x14a0c400
	s_addc_u32 s25, s5, 0
	s_mov_b32 m0, s91
	v_lshl_add_u64 v[254:255], v[246:247], 0, s[24:25]
	s_add_i32 s1, s89, s18
	global_load_lds_dwordx4 v[254:255], off
	s_add_u32 s24, s4, 0x149ec500
	s_addc_u32 s25, s5, 0
	s_mov_b32 m0, s1
	v_lshl_add_u64 v[254:255], v[248:249], 0, s[24:25]
	global_load_lds_dwordx4 v[254:255], off
	s_add_u32 s24, s4, 0x14a0c500
	s_addc_u32 s25, s5, 0
	s_add_i32 m0, s1, 0x2000
	v_lshl_add_u64 v[254:255], v[248:249], 0, s[24:25]
	global_load_lds_dwordx4 v[254:255], off
	s_add_u32 s4, s38, s88
	s_addc_u32 s5, s39, s87
	s_add_u32 s4, s4, s36
	s_addc_u32 s5, s5, s37
	s_mov_b32 m0, s92
	v_lshl_add_u64 v[254:255], v[250:251], 0, s[4:5]
	global_load_lds_dwordx4 v[254:255], off
	v_exp_f32_e32 v156, v156
	v_add_f32_e32 v146, v164, v146
	v_exp_f32_e32 v157, v157
	v_add_f32_e32 v146, v165, v146
	v_add_f32_e32 v146, v197, v146
	v_exp_f32_e32 v241, v147
	s_waitcnt lgkmcnt(0)
	v_mfma_f32_32x32x16_bf16 v[82:97], v[206:209], v[134:137], v[82:97]
	v_mfma_f32_32x32x16_bf16 v[66:81], v[210:213], v[134:137], v[66:81]
	ds_read_b128 v[208:211], v180 offset:49152
	ds_read_b128 v[212:215], v180 offset:57344
	s_waitcnt lgkmcnt(0)
	v_mfma_f32_32x32x16_bf16 v[82:97], v[208:211], v[130:133], v[82:97]
	v_mfma_f32_32x32x16_bf16 v[66:81], v[212:215], v[130:133], v[66:81]
	ds_read_b128 v[208:211], v182 offset:49152
	ds_read_b128 v[212:215], v182 offset:57344
	s_waitcnt lgkmcnt(0)
	v_mfma_f32_32x32x16_bf16 v[82:97], v[208:211], v[126:129], v[82:97]
	v_mfma_f32_32x32x16_bf16 v[66:81], v[212:215], v[126:129], v[66:81]
	ds_read_b128 v[210:213], v186 offset:49152
	ds_read_b128 v[232:235], v186 offset:57344
	s_waitcnt lgkmcnt(0)
	v_mfma_f32_32x32x16_bf16 v[82:97], v[210:213], v[122:125], v[82:97]
	v_mfma_f32_32x32x16_bf16 v[66:81], v[232:235], v[122:125], v[66:81]
	ds_read_b128 v[210:213], v188 offset:49152
	ds_read_b128 v[232:235], v188 offset:57344
	s_waitcnt lgkmcnt(0)
	v_mfma_f32_32x32x16_bf16 v[82:97], v[210:213], v[118:121], v[82:97]
	v_mfma_f32_32x32x16_bf16 v[66:81], v[232:235], v[118:121], v[66:81]
	ds_read_b128 v[212:215], v190 offset:49152
	ds_read_b128 v[232:235], v190 offset:57344
	s_waitcnt lgkmcnt(0)
	v_mfma_f32_32x32x16_bf16 v[82:97], v[212:215], v[114:117], v[82:97]
	v_mfma_f32_32x32x16_bf16 v[66:81], v[232:235], v[114:117], v[66:81]
	ds_read_b128 v[212:215], v192 offset:8192
	ds_read_b128 v[232:235], v192 offset:12288
	s_waitcnt lgkmcnt(0)
	v_mfma_f32_32x32x16_bf16 v[82:97], v[212:215], v[110:113], v[82:97]
	v_exp_f32_e32 v215, v163
	s_nop 0
	v_add_f32_e32 v146, v215, v146
	v_mfma_f32_32x32x16_bf16 v[66:81], v[232:235], v[110:113], v[66:81]
	ds_read_b128 v[232:235], v194 offset:8192
	ds_read_b128 v[236:239], v194 offset:12288
	v_add_f32_e32 v146, v156, v146
	v_add_f32_e32 v146, v157, v146
	s_waitcnt lgkmcnt(0)
	v_mfma_f32_32x32x16_bf16 v[82:97], v[232:235], v[106:109], v[82:97]
	v_mfma_f32_32x32x16_bf16 v[66:81], v[236:239], v[106:109], v[66:81]
	ds_read_b128 v[232:235], v196 offset:8192
	ds_read_b128 v[236:239], v196 offset:12288
	s_waitcnt lgkmcnt(0)
	v_mfma_f32_32x32x16_bf16 v[82:97], v[232:235], v[102:105], v[82:97]
	v_mfma_f32_32x32x16_bf16 v[66:81], v[236:239], v[102:105], v[66:81]
	ds_read_b128 v[232:235], v199 offset:8192
	ds_read_b128 v[236:239], v199 offset:12288
	s_waitcnt lgkmcnt(0)
	v_mfma_f32_32x32x16_bf16 v[82:97], v[232:235], v[98:101], v[82:97]
	v_exp_f32_e32 v232, v154
	v_exp_f32_e32 v233, v155
	v_exp_f32_e32 v234, v152
	v_exp_f32_e32 v235, v153
	v_add_f32_e32 v146, v232, v146
	v_add_f32_e32 v146, v233, v146
	v_add_f32_e32 v146, v234, v146
	v_mfma_f32_32x32x16_bf16 v[66:81], v[236:239], v[98:101], v[66:81]
	v_exp_f32_e32 v236, v150
	v_exp_f32_e32 v237, v151
	v_exp_f32_e32 v238, v148
	v_exp_f32_e32 v239, v149
	v_add_f32_e32 v146, v235, v146
	v_add_f32_e32 v146, v236, v146
	v_add_f32_e32 v146, v237, v146
	v_add_f32_e32 v146, v238, v146
	v_add_f32_e32 v146, v239, v146
	v_add_f32_e32 v146, v240, v146
	v_add_f32_e32 v162, v241, v146
	v_mov_b32_e32 v163, v162
	s_nop 1
	v_permlane32_swap_b32_e32 v162, v163
	v_cvt_pk_bf16_f32 v146, v229, v231
	v_cvt_pk_bf16_f32 v147, v227, v230
	v_cvt_pk_bf16_f32 v148, v226, v228
	v_cvt_pk_bf16_f32 v149, v224, v225
	v_cvt_pk_bf16_f32 v150, v221, v223
	v_cvt_pk_bf16_f32 v151, v220, v222
	v_cvt_pk_bf16_f32 v152, v217, v219
	v_cvt_pk_bf16_f32 v153, v216, v218
	v_cvt_pk_bf16_f32 v154, v164, v165
	v_cvt_pk_bf16_f32 v155, v197, v215
	v_cvt_pk_bf16_f32 v156, v156, v157
	v_cvt_pk_bf16_f32 v157, v232, v233
	v_cvt_pk_bf16_f32 v216, v234, v235
	v_cvt_pk_bf16_f32 v217, v236, v237
	v_cvt_pk_bf16_f32 v218, v238, v239
	v_cvt_pk_bf16_f32 v219, v240, v241
	s_nop 0
	v_permlane32_swap_b32_e32 v146, v148
	v_permlane32_swap_b32_e32 v147, v149
	v_permlane32_swap_b32_e32 v150, v152
	v_permlane32_swap_b32_e32 v151, v153
	v_permlane32_swap_b32_e32 v154, v156
	v_permlane32_swap_b32_e32 v155, v157
	v_permlane32_swap_b32_e32 v216, v218
	v_permlane32_swap_b32_e32 v217, v219
	s_lshl_b32 s24, s17, 14
	v_add_u32_e32 v197, s24, v200
	ds_read_b64_tr_b16 v[220:221], v197 offset:0
	ds_read_b64_tr_b16 v[222:223], v197 offset:0x800
	ds_read_b64_tr_b16 v[224:225], v197 offset:0x1000
	ds_read_b64_tr_b16 v[226:227], v197 offset:0x1800
	ds_read_b64_tr_b16 v[228:229], v197 offset:0x2000
	ds_read_b64_tr_b16 v[230:231], v197 offset:0x2800
	ds_read_b64_tr_b16 v[232:233], v197 offset:0x3000
	ds_read_b64_tr_b16 v[234:235], v197 offset:0x3800
	s_waitcnt lgkmcnt(0)
	s_nop 0
	v_mfma_f32_32x32x16_bf16 v[2:17], v[146:149], v[220:223], v[2:17]
	ds_read_b64_tr_b16 v[220:221], v197 offset:0x200
	ds_read_b64_tr_b16 v[222:223], v197 offset:0xa00
	v_max_f32_e32 v164, v83, v83
	v_max_f32_e32 v165, v82, v82
	v_max_f32_e32 v164, v165, v164
	v_max3_f32 v164, v164, v84, v85
	v_max3_f32 v164, v164, v86, v87
	v_mfma_f32_32x32x16_bf16 v[2:17], v[150:153], v[224:227], v[2:17]
	ds_read_b64_tr_b16 v[224:225], v197 offset:0x1200
	ds_read_b64_tr_b16 v[226:227], v197 offset:0x1a00
	v_max3_f32 v164, v164, v88, v89
	v_max3_f32 v164, v164, v90, v91
	v_max3_f32 v164, v164, v92, v93
	v_max3_f32 v164, v164, v94, v95
	v_max3_f32 v164, v164, v96, v97
	v_mfma_f32_32x32x16_bf16 v[2:17], v[154:157], v[228:231], v[2:17]
	ds_read_b64_tr_b16 v[228:229], v197 offset:0x2200
	ds_read_b64_tr_b16 v[230:231], v197 offset:0x2a00
	ds_read_b64_tr_b16 v[236:237], v197 offset:0x3200
	ds_read_b64_tr_b16 v[238:239], v197 offset:0x3a00
	s_waitcnt lgkmcnt(0)
	v_mfma_f32_32x32x16_bf16 v[2:17], v[216:219], v[232:235], v[2:17]
	v_mfma_f32_32x32x16_bf16 v[50:65], v[146:149], v[220:223], v[50:65]
	v_max3_f32 v164, v164, v66, v67
	v_max3_f32 v164, v164, v68, v69
	v_max3_f32 v164, v164, v70, v71
	v_max3_f32 v164, v164, v72, v73
	v_max3_f32 v164, v164, v74, v75
	v_max3_f32 v164, v164, v76, v77
	v_max3_f32 v164, v164, v78, v79
	v_mfma_f32_32x32x16_bf16 v[50:65], v[150:153], v[224:227], v[50:65]
	v_max3_f32 v164, v164, v80, v81
	v_mov_b32_e32 v165, v164
	s_nop 1
	v_permlane32_swap_b32_e32 v164, v165
	ds_read_b64_tr_b16 v[220:221], v197 offset:0x400
	v_max_f32_e32 v165, v165, v165
	v_max_f32_e32 v164, v164, v164
	v_mfma_f32_32x32x16_bf16 v[50:65], v[154:157], v[228:231], v[50:65]
	ds_read_b64_tr_b16 v[222:223], v197 offset:0xc00
	v_max_f32_e32 v164, v164, v165
	v_max_f32_e32 v165, v202, v202
	ds_read_b64_tr_b16 v[224:225], v197 offset:0x1400
	v_max_f32_e32 v165, v165, v164
	ds_read_b64_tr_b16 v[226:227], v197 offset:0x1c00
	v_sub_f32_e32 v215, v164, v202
	v_mfma_f32_32x32x16_bf16 v[50:65], v[216:219], v[236:239], v[50:65]
	v_sub_f32_e32 v164, v202, v165
	ds_read_b64_tr_b16 v[228:229], v197 offset:0x2400
	v_mul_f32_e32 v164, 0x3dd53b94, v164
	ds_read_b64_tr_b16 v[230:231], v197 offset:0x2c00
	v_exp_f32_e32 v164, v164
	ds_read_b64_tr_b16 v[232:233], v197 offset:0x3400
	v_cmp_ge_f32_e32 vcc, s77, v215
	ds_read_b64_tr_b16 v[234:235], v197 offset:0x3c00
	s_cmp_eq_u64 vcc, exec
	s_waitcnt lgkmcnt(0)
	s_cselect_b64 s[4:5], -1, 0
	v_cndmask_b32_e64 v164, v164, 1.0, s[4:5]
	v_mfma_f32_32x32x16_bf16 v[34:49], v[146:149], v[220:223], v[34:49]
	ds_read_b64_tr_b16 v[220:221], v197 offset:0x600
	ds_read_b64_tr_b16 v[222:223], v197 offset:0xe00
	v_mfma_f32_32x32x16_bf16 v[34:49], v[150:153], v[224:227], v[34:49]
	ds_read_b64_tr_b16 v[224:225], v197 offset:0x1600
	ds_read_b64_tr_b16 v[226:227], v197 offset:0x1e00
	v_mfma_f32_32x32x16_bf16 v[34:49], v[154:157], v[228:231], v[34:49]
	ds_read_b64_tr_b16 v[228:229], v197 offset:0x2600
	ds_read_b64_tr_b16 v[230:231], v197 offset:0x2e00
	ds_read_b64_tr_b16 v[236:237], v197 offset:0x3600
	ds_read_b64_tr_b16 v[238:239], v197 offset:0x3e00
	s_waitcnt lgkmcnt(0)
	v_mfma_f32_32x32x16_bf16 v[34:49], v[216:219], v[232:235], v[34:49]
	v_mfma_f32_32x32x16_bf16 v[18:33], v[146:149], v[220:223], v[18:33]
	v_cmp_gt_f32_e32 vcc, 1.0, v164
	v_mfma_f32_32x32x16_bf16 v[18:33], v[150:153], v[224:227], v[18:33]
	v_mfma_f32_32x32x16_bf16 v[18:33], v[154:157], v[228:231], v[18:33]
	v_mfma_f32_32x32x16_bf16 v[18:33], v[216:219], v[236:239], v[18:33]
	s_cbranch_vccz .LBB0_547
	s_and_saveexec_b64 s[0:1], s[2:3]
	ds_write_b32 v170, v164 offset:128
	s_or_b64 exec, exec, s[0:1]
	s_waitcnt lgkmcnt(0)
	ds_read_b128 v[146:149], v158 offset:224
	ds_read_b128 v[150:153], v158 offset:192
	ds_read_b128 v[154:157], v158 offset:160
	ds_read_b128 v[216:219], v158 offset:128
	s_waitcnt lgkmcnt(0)
	v_pk_mul_f32 v[16:17], v[16:17], v[148:149]
	v_pk_mul_f32 v[12:13], v[12:13], v[152:153]
	v_pk_mul_f32 v[8:9], v[8:9], v[156:157]
	v_pk_mul_f32 v[4:5], v[4:5], v[218:219]
	v_pk_mul_f32 v[14:15], v[14:15], v[146:147]
	v_pk_mul_f32 v[10:11], v[10:11], v[150:151]
	v_pk_mul_f32 v[6:7], v[6:7], v[154:155]
	v_pk_mul_f32 v[2:3], v[2:3], v[216:217]
	v_pk_mul_f32 v[64:65], v[64:65], v[148:149]
	v_pk_mul_f32 v[60:61], v[60:61], v[152:153]
	v_pk_mul_f32 v[56:57], v[56:57], v[156:157]
	v_pk_mul_f32 v[52:53], v[52:53], v[218:219]
	v_pk_mul_f32 v[62:63], v[62:63], v[146:147]
	v_pk_mul_f32 v[58:59], v[58:59], v[150:151]
	v_pk_mul_f32 v[54:55], v[54:55], v[154:155]
	v_pk_mul_f32 v[50:51], v[50:51], v[216:217]
	v_pk_mul_f32 v[48:49], v[48:49], v[148:149]
	v_pk_mul_f32 v[44:45], v[44:45], v[152:153]
	v_pk_mul_f32 v[40:41], v[40:41], v[156:157]
	v_pk_mul_f32 v[36:37], v[36:37], v[218:219]
	v_pk_mul_f32 v[46:47], v[46:47], v[146:147]
	v_pk_mul_f32 v[42:43], v[42:43], v[150:151]
	v_pk_mul_f32 v[38:39], v[38:39], v[154:155]
	v_pk_mul_f32 v[34:35], v[34:35], v[216:217]
	v_pk_mul_f32 v[32:33], v[32:33], v[148:149]
	v_pk_mul_f32 v[28:29], v[28:29], v[152:153]
	v_pk_mul_f32 v[24:25], v[24:25], v[156:157]
	v_pk_mul_f32 v[20:21], v[20:21], v[218:219]
	v_pk_mul_f32 v[30:31], v[30:31], v[146:147]
	v_pk_mul_f32 v[26:27], v[26:27], v[150:151]
	v_pk_mul_f32 v[22:23], v[22:23], v[154:155]
	v_pk_mul_f32 v[18:19], v[18:19], v[216:217]

.LBB0_553:
	v_cndmask_b32_e64 v202, v202, v165, s[4:5]
	v_mul_f32_e32 v146, 0xbdd53b94, v202
	v_fmamk_f32 v229, v82, 0x3dd53b94, v146
	v_fmamk_f32 v231, v83, 0x3dd53b94, v146
	v_fmamk_f32 v227, v84, 0x3dd53b94, v146
	v_fmamk_f32 v230, v85, 0x3dd53b94, v146
	v_fmamk_f32 v226, v86, 0x3dd53b94, v146
	v_fmamk_f32 v228, v87, 0x3dd53b94, v146
	v_fmamk_f32 v224, v88, 0x3dd53b94, v146
	v_fmamk_f32 v225, v89, 0x3dd53b94, v146
	v_fmamk_f32 v221, v90, 0x3dd53b94, v146
	v_fmamk_f32 v223, v91, 0x3dd53b94, v146
	v_fmamk_f32 v220, v92, 0x3dd53b94, v146
	v_fmamk_f32 v222, v93, 0x3dd53b94, v146
	v_fmamk_f32 v217, v94, 0x3dd53b94, v146
	v_fmamk_f32 v219, v95, 0x3dd53b94, v146
	v_fmamk_f32 v216, v96, 0x3dd53b94, v146
	v_fmamk_f32 v218, v97, 0x3dd53b94, v146
	s_add_u32 s88, s88, 0xf0000
	s_addc_u32 s87, s87, 0
	v_add_f32_e32 v82, v162, v163
	s_waitcnt vmcnt(0)
	s_add_u32 s20, s20, 0x80000
	v_fmac_f32_e32 v82, v201, v171
	v_add_f32_e32 v171, v232, v233
	s_addc_u32 s21, s21, 0
	s_add_i32 s19, s19, 2
	v_fmac_f32_e32 v171, v82, v164
	v_fma_f32 v164, v66, s34, v146
	v_fma_f32 v165, v67, s34, v146
	v_fma_f32 v162, v68, s34, v146
	v_fma_f32 v163, v69, s34, v146
	v_fma_f32 v156, v70, s34, v146
	v_fma_f32 v157, v71, s34, v146
	v_fma_f32 v154, v72, s34, v146
	v_fma_f32 v155, v73, s34, v146
	s_cmp_ge_u32 s19, s86
	s_mov_b32 s0, s22
	s_mov_b32 s22, s23
	v_mov_b32_e32 v201, v215
	s_waitcnt vmcnt(0)
	s_barrier
	s_cbranch_scc0 .LBB0_543
	v_fma_f32 v152, v74, s34, v146
	v_fma_f32 v153, v75, s34, v146
	v_fma_f32 v150, v76, s34, v146
	v_fma_f32 v151, v77, s34, v146
	v_fma_f32 v148, v78, s34, v146
	v_fma_f32 v149, v79, s34, v146
	v_fma_f32 v147, v81, s34, v146
	v_fma_f32 v146, v80, s34, v146
	v_exp_f32_e32 v229, v229
	v_exp_f32_e32 v231, v231
	v_exp_f32_e32 v227, v227
	v_exp_f32_e32 v230, v230
	v_exp_f32_e32 v226, v226
	v_exp_f32_e32 v228, v228
	v_exp_f32_e32 v224, v224
	v_exp_f32_e32 v225, v225
	v_exp_f32_e32 v221, v221
	v_exp_f32_e32 v223, v223
	v_exp_f32_e32 v220, v220
	v_exp_f32_e32 v222, v222
	v_exp_f32_e32 v217, v217
	v_exp_f32_e32 v219, v219
	v_exp_f32_e32 v216, v216
	v_exp_f32_e32 v218, v218
